# grid barrier waiters poll the top-level generation word directly (skip per-XCD generation hop)
# speedup vs baseline: 1.0054x; 1.0054x over previous
.LBB0_340:
	s_or_b64 exec, exec, s[6:7]
	v_cvt_f32_u32_e32 v4, v2
	s_waitcnt vmcnt(0)
	v_readfirstlane_b32 s4, v3
	v_sub_u32_e32 v3, 0, v2
	v_rcp_iflag_f32_e32 v4, v4
	v_add_u32_e32 v5, s4, v1
	v_mul_f32_e32 v4, 0x4f7ffffe, v4
	v_cvt_u32_f32_e32 v4, v4
	v_mul_lo_u32 v1, v3, v4
	v_mul_hi_u32 v1, v4, v1
	v_add_u32_e32 v1, v4, v1
	v_mul_hi_u32 v1, v5, v1
	v_mul_lo_u32 v3, v1, v2
	v_sub_u32_e32 v3, v5, v3
	v_add_u32_e32 v4, 1, v1
	v_cmp_ge_u32_e32 vcc, v3, v2
	s_nop 1
	v_cndmask_b32_e32 v1, v1, v4, vcc
	v_sub_u32_e32 v4, v3, v2
	v_cndmask_b32_e32 v3, v3, v4, vcc
	v_add_u32_e32 v4, 1, v1
	v_cmp_ge_u32_e32 vcc, v3, v2
	v_add_u32_e32 v3, 1, v5
	s_nop 0
	v_cndmask_b32_e32 v1, v1, v4, vcc
	v_mul_lo_u32 v4, v2, v1
	v_add_u32_e32 v2, v4, v2
	v_cmp_ne_u32_e32 vcc, v3, v2
	s_and_saveexec_b64 s[4:5], vcc
	s_xor_b64 s[4:5], exec, s[4:5]
	s_cbranch_execz .LBB0_354
	s_waitcnt lgkmcnt(0)
	v_mov_b32_e32 v0, 0x2000
	s_add_u32 s8, s76, 0x3500
	s_addc_u32 s9, s77, 0
	v_mov_b32_e32 v0, 0
	s_nop 3
	global_load_dword v0, v0, s[8:9] sc1
	s_waitcnt vmcnt(0)
	v_cmp_eq_u32_e32 vcc, v0, v1
	s_and_saveexec_b64 s[6:7], vcc
	s_cbranch_execz .LBB0_353
	s_mov_b32 s20, 1
	s_mov_b64 s[10:11], 0
	v_mov_b32_e32 v0, 0
	s_branch .LBB0_344

.LBB0_698:
	s_or_b64 exec, exec, s[6:7]
	v_cvt_f32_u32_e32 v4, v2
	s_waitcnt vmcnt(0)
	v_readfirstlane_b32 s4, v3
	v_sub_u32_e32 v3, 0, v2
	v_rcp_iflag_f32_e32 v4, v4
	v_add_u32_e32 v5, s4, v1
	v_mul_f32_e32 v4, 0x4f7ffffe, v4
	v_cvt_u32_f32_e32 v4, v4
	v_mul_lo_u32 v1, v3, v4
	v_mul_hi_u32 v1, v4, v1
	v_add_u32_e32 v1, v4, v1
	v_mul_hi_u32 v1, v5, v1
	v_mul_lo_u32 v3, v1, v2
	v_sub_u32_e32 v3, v5, v3
	v_add_u32_e32 v4, 1, v1
	v_sub_u32_e32 v6, v3, v2
	v_cmp_ge_u32_e32 vcc, v3, v2
	s_nop 1
	v_cndmask_b32_e32 v1, v1, v4, vcc
	v_cndmask_b32_e32 v3, v3, v6, vcc
	v_add_u32_e32 v4, 1, v1
	v_cmp_ge_u32_e32 vcc, v3, v2
	v_add_u32_e32 v3, 1, v5
	s_nop 0
	v_cndmask_b32_e32 v1, v1, v4, vcc
	v_mul_lo_u32 v4, v2, v1
	v_add_u32_e32 v2, v4, v2
	v_cmp_ne_u32_e32 vcc, v3, v2
	s_and_saveexec_b64 s[4:5], vcc
	s_xor_b64 s[4:5], exec, s[4:5]
	s_cbranch_execz .LBB0_712
	s_waitcnt lgkmcnt(0)
	s_add_u32 s12, s76, 0x3500
	s_addc_u32 s13, s77, 0
	v_mov_b32_e32 v0, 0
	s_nop 3
	global_load_dword v0, v0, s[12:13] sc1
	s_waitcnt vmcnt(0)
	v_cmp_eq_u32_e32 vcc, v0, v1
	s_and_saveexec_b64 s[6:7], vcc
	s_cbranch_execz .LBB0_711
	s_mov_b32 s24, 1
	s_mov_b64 s[14:15], 0
	s_branch .LBB0_702

.LBB0_762:
	s_or_b64 exec, exec, s[6:7]
	v_cvt_f32_u32_e32 v4, v2
	s_waitcnt vmcnt(0)
	v_readfirstlane_b32 s4, v3
	v_sub_u32_e32 v3, 0, v2
	v_rcp_iflag_f32_e32 v4, v4
	v_add_u32_e32 v5, s4, v1
	v_mul_f32_e32 v4, 0x4f7ffffe, v4
	v_cvt_u32_f32_e32 v4, v4
	v_mul_lo_u32 v1, v3, v4
	v_mul_hi_u32 v1, v4, v1
	v_add_u32_e32 v1, v4, v1
	v_mul_hi_u32 v1, v5, v1
	v_mul_lo_u32 v3, v1, v2
	v_sub_u32_e32 v3, v5, v3
	v_add_u32_e32 v4, 1, v1
	v_cmp_ge_u32_e32 vcc, v3, v2
	s_nop 1
	v_cndmask_b32_e32 v1, v1, v4, vcc
	v_sub_u32_e32 v4, v3, v2
	v_cndmask_b32_e32 v3, v3, v4, vcc
	v_add_u32_e32 v4, 1, v1
	v_cmp_ge_u32_e32 vcc, v3, v2
	v_add_u32_e32 v3, 1, v5
	s_nop 0
	v_cndmask_b32_e32 v1, v1, v4, vcc
	v_mul_lo_u32 v4, v2, v1
	v_add_u32_e32 v2, v4, v2
	v_cmp_ne_u32_e32 vcc, v3, v2
	s_and_saveexec_b64 s[4:5], vcc
	s_xor_b64 s[4:5], exec, s[4:5]
	s_cbranch_execz .LBB0_776
	s_waitcnt lgkmcnt(0)
	s_add_u32 s12, s76, 0x3500
	s_addc_u32 s13, s77, 0
	v_mov_b32_e32 v0, 0
	s_nop 3
	global_load_dword v0, v0, s[12:13] sc1
	s_waitcnt vmcnt(0)
	v_cmp_eq_u32_e32 vcc, v0, v1
	s_and_saveexec_b64 s[6:7], vcc
	s_cbranch_execz .LBB0_775
	s_mov_b32 s24, 1
	s_mov_b64 s[14:15], 0
	s_branch .LBB0_766

.LBB0_840:
	s_or_b64 exec, exec, s[6:7]
	v_cvt_f32_u32_e32 v4, v2
	s_waitcnt vmcnt(0)
	v_readfirstlane_b32 s4, v3
	v_sub_u32_e32 v3, 0, v2
	v_rcp_iflag_f32_e32 v4, v4
	v_add_u32_e32 v5, s4, v1
	v_mul_f32_e32 v4, 0x4f7ffffe, v4
	v_cvt_u32_f32_e32 v4, v4
	v_mul_lo_u32 v1, v3, v4
	v_mul_hi_u32 v1, v4, v1
	v_add_u32_e32 v1, v4, v1
	v_mul_hi_u32 v1, v5, v1
	v_mul_lo_u32 v3, v1, v2
	v_sub_u32_e32 v3, v5, v3
	v_add_u32_e32 v4, 1, v1
	v_cmp_ge_u32_e32 vcc, v3, v2
	s_nop 1
	v_cndmask_b32_e32 v1, v1, v4, vcc
	v_sub_u32_e32 v4, v3, v2
	v_cndmask_b32_e32 v3, v3, v4, vcc
	v_add_u32_e32 v4, 1, v1
	v_cmp_ge_u32_e32 vcc, v3, v2
	v_add_u32_e32 v3, 1, v5
	s_nop 0
	v_cndmask_b32_e32 v1, v1, v4, vcc
	v_mul_lo_u32 v4, v2, v1
	v_add_u32_e32 v2, v4, v2
	v_cmp_ne_u32_e32 vcc, v3, v2
	s_and_saveexec_b64 s[4:5], vcc
	s_xor_b64 s[4:5], exec, s[4:5]
	s_cbranch_execz .LBB0_854
	s_waitcnt lgkmcnt(0)
	s_add_u32 s8, s76, 0x3500
	s_addc_u32 s9, s77, 0
	v_mov_b32_e32 v0, 0
	s_nop 3
	global_load_dword v0, v0, s[8:9] sc1
	s_waitcnt vmcnt(0)
	v_cmp_eq_u32_e32 vcc, v0, v1
	s_and_saveexec_b64 s[6:7], vcc
	s_cbranch_execz .LBB0_853
	s_mov_b32 s20, 1
	s_mov_b64 s[10:11], 0
	s_branch .LBB0_844

.LBB0_1260:
	s_or_b64 exec, exec, s[6:7]
	v_cvt_f32_u32_e32 v4, v2
	s_waitcnt vmcnt(0)
	v_readfirstlane_b32 s4, v3
	v_sub_u32_e32 v3, 0, v2
	v_rcp_iflag_f32_e32 v4, v4
	v_add_u32_e32 v5, s4, v1
	v_mul_f32_e32 v4, 0x4f7ffffe, v4
	v_cvt_u32_f32_e32 v4, v4
	v_mul_lo_u32 v1, v3, v4
	v_mul_hi_u32 v1, v4, v1
	v_add_u32_e32 v1, v4, v1
	v_mul_hi_u32 v1, v5, v1
	v_mul_lo_u32 v3, v1, v2
	v_sub_u32_e32 v3, v5, v3
	v_add_u32_e32 v4, 1, v1
	v_cmp_ge_u32_e32 vcc, v3, v2
	s_nop 1
	v_cndmask_b32_e32 v1, v1, v4, vcc
	v_sub_u32_e32 v4, v3, v2
	v_cndmask_b32_e32 v3, v3, v4, vcc
	v_add_u32_e32 v4, 1, v1
	v_cmp_ge_u32_e32 vcc, v3, v2
	v_add_u32_e32 v3, 1, v5
	s_nop 0
	v_cndmask_b32_e32 v1, v1, v4, vcc
	v_mul_lo_u32 v4, v2, v1
	v_add_u32_e32 v2, v4, v2
	v_cmp_ne_u32_e32 vcc, v3, v2
	s_and_saveexec_b64 s[4:5], vcc
	s_xor_b64 s[4:5], exec, s[4:5]
	s_cbranch_execz .LBB0_1274
	s_waitcnt lgkmcnt(0)
	s_add_u32 s8, s76, 0x3500
	s_addc_u32 s9, s77, 0
	v_mov_b32_e32 v0, 0
	s_nop 3
	global_load_dword v0, v0, s[8:9] sc1
	s_waitcnt vmcnt(0)
	v_cmp_eq_u32_e32 vcc, v0, v1
	s_and_saveexec_b64 s[6:7], vcc
	s_cbranch_execz .LBB0_1273
	s_mov_b32 s19, 1
	s_mov_b64 s[10:11], 0
	s_branch .LBB0_1264

.LBB0_1866:
	s_or_b64 exec, exec, s[8:9]
	v_cvt_f32_u32_e32 v4, v2
	s_waitcnt vmcnt(0)
	v_readfirstlane_b32 s6, v3
	v_sub_u32_e32 v3, 0, v2
	v_rcp_iflag_f32_e32 v4, v4
	v_add_u32_e32 v5, s6, v1
	v_mul_f32_e32 v4, 0x4f7ffffe, v4
	v_cvt_u32_f32_e32 v4, v4
	v_mul_lo_u32 v1, v3, v4
	v_mul_hi_u32 v1, v4, v1
	v_add_u32_e32 v1, v4, v1
	v_mul_hi_u32 v1, v5, v1
	v_mul_lo_u32 v3, v1, v2
	v_sub_u32_e32 v3, v5, v3
	v_add_u32_e32 v4, 1, v1
	v_cmp_ge_u32_e32 vcc, v3, v2
	s_nop 1
	v_cndmask_b32_e32 v1, v1, v4, vcc
	v_sub_u32_e32 v4, v3, v2
	v_cndmask_b32_e32 v3, v3, v4, vcc
	v_add_u32_e32 v4, 1, v1
	v_cmp_ge_u32_e32 vcc, v3, v2
	v_add_u32_e32 v3, 1, v5
	s_nop 0
	v_cndmask_b32_e32 v1, v1, v4, vcc
	v_mul_lo_u32 v4, v2, v1
	v_add_u32_e32 v2, v4, v2
	v_cmp_ne_u32_e32 vcc, v3, v2
	s_and_saveexec_b64 s[6:7], vcc
	s_xor_b64 s[6:7], exec, s[6:7]
	s_cbranch_execz .LBB0_1880
	s_waitcnt lgkmcnt(0)
	s_add_u32 s10, s76, 0x3500
	s_addc_u32 s11, s77, 0
	v_mov_b32_e32 v0, 0
	s_nop 3
	global_load_dword v0, v0, s[10:11] sc1
	s_waitcnt vmcnt(0)
	v_cmp_eq_u32_e32 vcc, v0, v1
	s_and_saveexec_b64 s[8:9], vcc
	s_cbranch_execz .LBB0_1879
	s_mov_b32 s23, 1
	s_mov_b64 s[12:13], 0
	s_branch .LBB0_1870

.LBB0_1989:
	s_or_b64 exec, exec, s[8:9]
	v_cvt_f32_u32_e32 v4, v2
	s_waitcnt vmcnt(0)
	v_readfirstlane_b32 s6, v3
	v_sub_u32_e32 v3, 0, v2
	v_rcp_iflag_f32_e32 v4, v4
	v_add_u32_e32 v5, s6, v1
	v_mul_f32_e32 v4, 0x4f7ffffe, v4
	v_cvt_u32_f32_e32 v4, v4
	v_mul_lo_u32 v1, v3, v4
	v_mul_hi_u32 v1, v4, v1
	v_add_u32_e32 v1, v4, v1
	v_mul_hi_u32 v1, v5, v1
	v_mul_lo_u32 v3, v1, v2
	v_sub_u32_e32 v3, v5, v3
	v_add_u32_e32 v4, 1, v1
	v_cmp_ge_u32_e32 vcc, v3, v2
	s_nop 1
	v_cndmask_b32_e32 v1, v1, v4, vcc
	v_sub_u32_e32 v4, v3, v2
	v_cndmask_b32_e32 v3, v3, v4, vcc
	v_add_u32_e32 v4, 1, v1
	v_cmp_ge_u32_e32 vcc, v3, v2
	v_add_u32_e32 v3, 1, v5
	s_nop 0
	v_cndmask_b32_e32 v1, v1, v4, vcc
	v_mul_lo_u32 v4, v2, v1
	v_add_u32_e32 v2, v4, v2
	v_cmp_ne_u32_e32 vcc, v3, v2
	s_and_saveexec_b64 s[6:7], vcc
	s_xor_b64 s[6:7], exec, s[6:7]
	s_cbranch_execz .LBB0_2003
	s_waitcnt lgkmcnt(0)
	s_add_u32 s10, s76, 0x3500
	s_addc_u32 s11, s77, 0
	v_mov_b32_e32 v0, 0
	s_nop 3
	global_load_dword v0, v0, s[10:11] sc1
	s_waitcnt vmcnt(0)
	v_cmp_eq_u32_e32 vcc, v0, v1
	s_and_saveexec_b64 s[8:9], vcc
	s_cbranch_execz .LBB0_2002
	s_mov_b32 s22, 1
	s_mov_b64 s[12:13], 0
	s_branch .LBB0_1993
